# P58: input-conversion row pass (P0b) - the four modulation-vector loads of a row issued together, one wait instead of a 4-step load/store ladder
# speedup vs baseline: 1.0108x; 1.0108x over previous
.LBB0_249:
	s_min_i32 s7, s6, 0x8000
	s_ashr_i32 s7, s7, 11
	s_mul_hi_i32 s9, s7, 0x6000
	s_mulk_i32 s7, 0x6000
	s_add_u32 s7, s44, s7
	s_addc_u32 s9, s45, s9
	s_add_u32 s12, s7, 0x1000
	s_addc_u32 s13, s9, 0
	v_lshl_add_u64 v[66:67], v[116:117], 2, s[12:13]
	global_load_dwordx4 v[128:131], v[66:67], off
	v_lshl_add_u64 v[212:213], v[118:119], 2, s[12:13]
	global_load_dwordx4 v[200:203], v[212:213], off
	v_lshl_add_u64 v[212:213], v[120:121], 2, s[12:13]
	global_load_dwordx4 v[204:207], v[212:213], off
	v_lshl_add_u64 v[212:213], v[122:123], 2, s[12:13]
	global_load_dwordx4 v[208:211], v[212:213], off
	s_ashr_i32 s7, s6, 31
	s_lshl_b64 s[14:15], s[6:7], 11
	v_lshl_add_u64 v[132:133], v[126:127], 0, s[14:15]
	s_waitcnt vmcnt(7)
	v_mul_f32_e32 v64, v17, v17
	s_waitcnt vmcnt(6)
	v_mul_f32_e32 v134, v23, v23
	s_waitcnt vmcnt(5)
	v_mul_f32_e32 v135, v25, v25
	v_mul_f32_e32 v136, v27, v27
	v_fmac_f32_e32 v64, v16, v16
	v_fmac_f32_e32 v134, v22, v22
	s_waitcnt vmcnt(4)
	v_mul_f32_e32 v137, v29, v29
	v_mul_f32_e32 v138, v31, v31
	v_fmac_f32_e32 v135, v24, v24
	v_fmac_f32_e32 v136, v26, v26
	v_fmac_f32_e32 v137, v28, v28
	v_fmac_f32_e32 v138, v30, v30
	s_waitcnt vmcnt(0)
	v_pk_add_f32 v[128:129], v[128:129], 1.0 op_sel_hi:[1,0]
	v_pk_add_f32 v[130:131], v[130:131], 1.0 op_sel_hi:[1,0]
	v_pk_mul_f32 v[128:129], v[0:1], v[128:129]
	v_pk_mul_f32 v[130:131], v[2:3], v[130:131]
	v_pk_mul_f32 v[128:129], v[16:17], v[128:129]
	v_pk_mul_f32 v[130:131], v[18:19], v[130:131]
	v_cvt_pk_bf16_f32 v128, v128, v129
	s_nop 0
	v_cvt_pk_bf16_f32 v129, v130, v131
	global_store_dwordx2 v[132:133], v[128:129], off
	v_pk_add_f32 v[200:201], v[200:201], 1.0 op_sel_hi:[1,0]
	v_pk_add_f32 v[202:203], v[202:203], 1.0 op_sel_hi:[1,0]
	v_pk_mul_f32 v[200:201], v[4:5], v[200:201]
	v_pk_mul_f32 v[202:203], v[6:7], v[202:203]
	v_pk_mul_f32 v[200:201], v[20:21], v[200:201]
	v_pk_mul_f32 v[202:203], v[22:23], v[202:203]
	v_cvt_pk_bf16_f32 v200, v200, v201
	s_nop 0
	v_cvt_pk_bf16_f32 v201, v202, v203
	global_store_dwordx2 v[132:133], v[200:201], off offset:512
	v_pk_add_f32 v[204:205], v[204:205], 1.0 op_sel_hi:[1,0]
	v_pk_add_f32 v[206:207], v[206:207], 1.0 op_sel_hi:[1,0]
	v_pk_mul_f32 v[204:205], v[8:9], v[204:205]
	v_pk_mul_f32 v[206:207], v[10:11], v[206:207]
	v_pk_mul_f32 v[204:205], v[24:25], v[204:205]
	v_pk_mul_f32 v[206:207], v[26:27], v[206:207]
	v_cvt_pk_bf16_f32 v204, v204, v205
	s_nop 0
	v_cvt_pk_bf16_f32 v205, v206, v207
	global_store_dwordx2 v[132:133], v[204:205], off offset:1024
	v_mul_f32_e32 v66, v19, v19
	v_mul_f32_e32 v67, v21, v21
	v_fmac_f32_e32 v66, v18, v18
	v_fmac_f32_e32 v67, v20, v20
	v_add_f32_e32 v64, v64, v66
	v_add_f32_e32 v66, v67, v134
	v_add_f32_e32 v67, v135, v136
	v_add_f32_e32 v64, v64, v66
	v_add_f32_e32 v134, v137, v138
	v_add_f32_e32 v64, v64, v67
	v_add_f32_e32 v64, v64, v134
	s_nop 1
	v_add_f32_dpp v64, v64, v64 quad_perm:[1,0,3,2] row_mask:0xf bank_mask:0xf
	s_nop 1
	v_add_f32_dpp v64, v64, v64 quad_perm:[2,3,0,1] row_mask:0xf bank_mask:0xf
	s_nop 1
	v_add_f32_dpp v64, v64, v64 row_half_mirror row_mask:0xf bank_mask:0xf
	s_nop 1
	v_add_f32_dpp v64, v64, v64 row_mirror row_mask:0xf bank_mask:0xf
	ds_swizzle_b32 v66, v64 offset:swizzle(SWAP,16)
	s_waitcnt lgkmcnt(0)
	v_add_f32_e32 v64, v64, v66
	v_mov_b32_e32 v66, v64
	s_nop 1
	v_permlane32_swap_b32_e32 v64, v66
	v_pk_add_f32 v[208:209], v[208:209], 1.0 op_sel_hi:[1,0]
	v_pk_add_f32 v[210:211], v[210:211], 1.0 op_sel_hi:[1,0]
	v_pk_mul_f32 v[208:209], v[12:13], v[208:209]
	v_pk_mul_f32 v[210:211], v[14:15], v[210:211]
	v_pk_mul_f32 v[208:209], v[28:29], v[208:209]
	v_pk_mul_f32 v[210:211], v[30:31], v[210:211]
	v_cvt_pk_bf16_f32 v208, v208, v209
	s_nop 0
	v_cvt_pk_bf16_f32 v209, v210, v211
	global_store_dwordx2 v[132:133], v[208:209], off offset:1536
	s_and_saveexec_b64 s[12:13], s[2:3]
	s_cbranch_execz .LBB0_255
	v_add_f32_e32 v64, v64, v66
	s_lshl_b64 s[14:15], s[6:7], 6
	v_cndmask_b32_e64 v64, 0, v64, s[4:5]
	v_lshl_add_u64 v[128:129], v[124:125], 0, s[14:15]
	v_mov_b32_e32 v66, v65
	v_mov_b32_e32 v67, v65
	global_store_dwordx4 v[128:129], v[64:67], off
	s_or_b64 exec, exec, s[12:13]
	s_add_i32 s12, s26, s6
	s_cmp_gt_i32 s12, 0x8fff
	s_cbranch_scc0 .LBB0_256

.LBB0_252:
	s_min_i32 s7, s12, 0x8000
	s_ashr_i32 s7, s7, 11
	s_mul_hi_i32 s9, s7, 0x6000
	s_mulk_i32 s7, 0x6000
	s_add_u32 s7, s44, s7
	s_addc_u32 s9, s45, s9
	s_add_u32 s14, s7, 0x1000
	s_addc_u32 s15, s9, 0
	v_lshl_add_u64 v[66:67], v[116:117], 2, s[14:15]
	global_load_dwordx4 v[128:131], v[66:67], off
	v_lshl_add_u64 v[212:213], v[118:119], 2, s[14:15]
	global_load_dwordx4 v[200:203], v[212:213], off
	v_lshl_add_u64 v[212:213], v[120:121], 2, s[14:15]
	global_load_dwordx4 v[204:207], v[212:213], off
	v_lshl_add_u64 v[212:213], v[122:123], 2, s[14:15]
	global_load_dwordx4 v[208:211], v[212:213], off
	s_ashr_i32 s13, s12, 31
	s_lshl_b64 s[20:21], s[12:13], 11
	v_lshl_add_u64 v[132:133], v[126:127], 0, s[20:21]
	v_mul_f32_e32 v64, v49, v49
	v_mul_f32_e32 v134, v55, v55
	v_mul_f32_e32 v135, v57, v57
	v_mul_f32_e32 v136, v59, v59
	v_fmac_f32_e32 v64, v48, v48
	v_fmac_f32_e32 v134, v54, v54
	v_mul_f32_e32 v137, v61, v61
	v_mul_f32_e32 v138, v63, v63
	v_fmac_f32_e32 v135, v56, v56
	v_fmac_f32_e32 v136, v58, v58
	v_fmac_f32_e32 v137, v60, v60
	v_fmac_f32_e32 v138, v62, v62
	s_waitcnt vmcnt(0)
	v_pk_add_f32 v[128:129], v[128:129], 1.0 op_sel_hi:[1,0]
	v_pk_add_f32 v[130:131], v[130:131], 1.0 op_sel_hi:[1,0]
	v_pk_mul_f32 v[128:129], v[0:1], v[128:129]
	v_pk_mul_f32 v[130:131], v[2:3], v[130:131]
	v_pk_mul_f32 v[128:129], v[48:49], v[128:129]
	v_pk_mul_f32 v[130:131], v[50:51], v[130:131]
	v_cvt_pk_bf16_f32 v128, v128, v129
	s_nop 0
	v_cvt_pk_bf16_f32 v129, v130, v131
	global_store_dwordx2 v[132:133], v[128:129], off
	v_pk_add_f32 v[200:201], v[200:201], 1.0 op_sel_hi:[1,0]
	v_pk_add_f32 v[202:203], v[202:203], 1.0 op_sel_hi:[1,0]
	v_pk_mul_f32 v[200:201], v[4:5], v[200:201]
	v_pk_mul_f32 v[202:203], v[6:7], v[202:203]
	v_pk_mul_f32 v[200:201], v[52:53], v[200:201]
	v_pk_mul_f32 v[202:203], v[54:55], v[202:203]
	v_cvt_pk_bf16_f32 v200, v200, v201
	s_nop 0
	v_cvt_pk_bf16_f32 v201, v202, v203
	global_store_dwordx2 v[132:133], v[200:201], off offset:512
	v_pk_add_f32 v[204:205], v[204:205], 1.0 op_sel_hi:[1,0]
	v_pk_add_f32 v[206:207], v[206:207], 1.0 op_sel_hi:[1,0]
	v_pk_mul_f32 v[204:205], v[8:9], v[204:205]
	v_pk_mul_f32 v[206:207], v[10:11], v[206:207]
	v_pk_mul_f32 v[204:205], v[56:57], v[204:205]
	v_pk_mul_f32 v[206:207], v[58:59], v[206:207]
	v_cvt_pk_bf16_f32 v204, v204, v205
	s_nop 0
	v_cvt_pk_bf16_f32 v205, v206, v207
	global_store_dwordx2 v[132:133], v[204:205], off offset:1024
	v_mul_f32_e32 v66, v51, v51
	v_mul_f32_e32 v67, v53, v53
	v_fmac_f32_e32 v66, v50, v50
	v_fmac_f32_e32 v67, v52, v52
	v_add_f32_e32 v64, v64, v66
	v_add_f32_e32 v66, v67, v134
	v_add_f32_e32 v67, v135, v136
	v_add_f32_e32 v64, v64, v66
	v_add_f32_e32 v134, v137, v138
	v_add_f32_e32 v64, v64, v67
	v_add_f32_e32 v64, v64, v134
	s_nop 1
	v_add_f32_dpp v64, v64, v64 quad_perm:[1,0,3,2] row_mask:0xf bank_mask:0xf
	s_nop 1
	v_add_f32_dpp v64, v64, v64 quad_perm:[2,3,0,1] row_mask:0xf bank_mask:0xf
	s_nop 1
	v_add_f32_dpp v64, v64, v64 row_half_mirror row_mask:0xf bank_mask:0xf
	s_nop 1
	v_add_f32_dpp v64, v64, v64 row_mirror row_mask:0xf bank_mask:0xf
	ds_swizzle_b32 v66, v64 offset:swizzle(SWAP,16)
	s_waitcnt lgkmcnt(0)
	v_add_f32_e32 v64, v64, v66
	v_mov_b32_e32 v66, v64
	s_nop 1
	v_permlane32_swap_b32_e32 v64, v66
	v_pk_add_f32 v[208:209], v[208:209], 1.0 op_sel_hi:[1,0]
	v_pk_add_f32 v[210:211], v[210:211], 1.0 op_sel_hi:[1,0]
	v_pk_mul_f32 v[208:209], v[12:13], v[208:209]
	v_pk_mul_f32 v[210:211], v[14:15], v[210:211]
	v_pk_mul_f32 v[208:209], v[60:61], v[208:209]
	v_pk_mul_f32 v[210:211], v[62:63], v[210:211]
	v_cvt_pk_bf16_f32 v208, v208, v209
	s_nop 0
	v_cvt_pk_bf16_f32 v209, v210, v211
	global_store_dwordx2 v[132:133], v[208:209], off offset:1536
	s_and_saveexec_b64 s[14:15], s[2:3]
	s_cbranch_execz .LBB0_254
	v_add_f32_e32 v64, v64, v66
	s_lshl_b64 s[12:13], s[12:13], 6
	v_cndmask_b32_e64 v64, 0, v64, s[4:5]
	v_lshl_add_u64 v[128:129], v[124:125], 0, s[12:13]
	v_mov_b32_e32 v66, v65
	v_mov_b32_e32 v67, v65
	global_store_dwordx4 v[128:129], v[64:67], off

.LBB0_256:
	s_min_i32 s7, s12, 0x8000
	s_ashr_i32 s7, s7, 11
	s_mul_hi_i32 s9, s7, 0x6000
	s_mulk_i32 s7, 0x6000
	s_add_u32 s7, s44, s7
	s_addc_u32 s9, s45, s9
	s_add_u32 s14, s7, 0x1000
	s_addc_u32 s15, s9, 0
	v_lshl_add_u64 v[66:67], v[116:117], 2, s[14:15]
	global_load_dwordx4 v[128:131], v[66:67], off
	v_lshl_add_u64 v[212:213], v[118:119], 2, s[14:15]
	global_load_dwordx4 v[200:203], v[212:213], off
	v_lshl_add_u64 v[212:213], v[120:121], 2, s[14:15]
	global_load_dwordx4 v[204:207], v[212:213], off
	v_lshl_add_u64 v[212:213], v[122:123], 2, s[14:15]
	global_load_dwordx4 v[208:211], v[212:213], off
	s_ashr_i32 s13, s12, 31
	s_lshl_b64 s[20:21], s[12:13], 11
	v_lshl_add_u64 v[132:133], v[126:127], 0, s[20:21]
	v_mul_f32_e32 v64, v33, v33
	v_mul_f32_e32 v134, v39, v39
	v_mul_f32_e32 v135, v41, v41
	v_mul_f32_e32 v136, v43, v43
	v_fmac_f32_e32 v64, v32, v32
	v_fmac_f32_e32 v134, v38, v38
	v_mul_f32_e32 v137, v45, v45
	v_mul_f32_e32 v138, v47, v47
	v_fmac_f32_e32 v135, v40, v40
	v_fmac_f32_e32 v136, v42, v42
	v_fmac_f32_e32 v137, v44, v44
	v_fmac_f32_e32 v138, v46, v46
	s_waitcnt vmcnt(0)
	v_pk_add_f32 v[128:129], v[128:129], 1.0 op_sel_hi:[1,0]
	v_pk_add_f32 v[130:131], v[130:131], 1.0 op_sel_hi:[1,0]
	v_pk_mul_f32 v[128:129], v[0:1], v[128:129]
	v_pk_mul_f32 v[130:131], v[2:3], v[130:131]
	v_pk_mul_f32 v[128:129], v[32:33], v[128:129]
	v_pk_mul_f32 v[130:131], v[34:35], v[130:131]
	v_cvt_pk_bf16_f32 v128, v128, v129
	s_nop 0
	v_cvt_pk_bf16_f32 v129, v130, v131
	global_store_dwordx2 v[132:133], v[128:129], off
	v_pk_add_f32 v[200:201], v[200:201], 1.0 op_sel_hi:[1,0]
	v_pk_add_f32 v[202:203], v[202:203], 1.0 op_sel_hi:[1,0]
	v_pk_mul_f32 v[200:201], v[4:5], v[200:201]
	v_pk_mul_f32 v[202:203], v[6:7], v[202:203]
	v_pk_mul_f32 v[200:201], v[36:37], v[200:201]
	v_pk_mul_f32 v[202:203], v[38:39], v[202:203]
	v_cvt_pk_bf16_f32 v200, v200, v201
	s_nop 0
	v_cvt_pk_bf16_f32 v201, v202, v203
	global_store_dwordx2 v[132:133], v[200:201], off offset:512
	v_pk_add_f32 v[204:205], v[204:205], 1.0 op_sel_hi:[1,0]
	v_pk_add_f32 v[206:207], v[206:207], 1.0 op_sel_hi:[1,0]
	v_pk_mul_f32 v[204:205], v[8:9], v[204:205]
	v_pk_mul_f32 v[206:207], v[10:11], v[206:207]
	v_pk_mul_f32 v[204:205], v[40:41], v[204:205]
	v_pk_mul_f32 v[206:207], v[42:43], v[206:207]
	v_cvt_pk_bf16_f32 v204, v204, v205
	s_nop 0
	v_cvt_pk_bf16_f32 v205, v206, v207
	global_store_dwordx2 v[132:133], v[204:205], off offset:1024
	v_mul_f32_e32 v66, v35, v35
	v_mul_f32_e32 v67, v37, v37
	v_fmac_f32_e32 v66, v34, v34
	v_fmac_f32_e32 v67, v36, v36
	v_add_f32_e32 v64, v64, v66
	v_add_f32_e32 v66, v67, v134
	v_add_f32_e32 v67, v135, v136
	v_add_f32_e32 v64, v64, v66
	v_add_f32_e32 v134, v137, v138
	v_add_f32_e32 v64, v64, v67
	v_add_f32_e32 v64, v64, v134
	s_nop 1
	v_add_f32_dpp v64, v64, v64 quad_perm:[1,0,3,2] row_mask:0xf bank_mask:0xf
	s_nop 1
	v_add_f32_dpp v64, v64, v64 quad_perm:[2,3,0,1] row_mask:0xf bank_mask:0xf
	s_nop 1
	v_add_f32_dpp v64, v64, v64 row_half_mirror row_mask:0xf bank_mask:0xf
	s_nop 1
	v_add_f32_dpp v64, v64, v64 row_mirror row_mask:0xf bank_mask:0xf
	ds_swizzle_b32 v66, v64 offset:swizzle(SWAP,16)
	s_waitcnt lgkmcnt(0)
	v_add_f32_e32 v64, v64, v66
	v_mov_b32_e32 v66, v64
	s_nop 1
	v_permlane32_swap_b32_e32 v64, v66
	v_pk_add_f32 v[208:209], v[208:209], 1.0 op_sel_hi:[1,0]
	v_pk_add_f32 v[210:211], v[210:211], 1.0 op_sel_hi:[1,0]
	v_pk_mul_f32 v[208:209], v[12:13], v[208:209]
	v_pk_mul_f32 v[210:211], v[14:15], v[210:211]
	v_pk_mul_f32 v[208:209], v[44:45], v[208:209]
	v_pk_mul_f32 v[210:211], v[46:47], v[210:211]
	v_cvt_pk_bf16_f32 v208, v208, v209
	s_nop 0
	v_cvt_pk_bf16_f32 v209, v210, v211
	global_store_dwordx2 v[132:133], v[208:209], off offset:1536
	s_and_saveexec_b64 s[14:15], s[2:3]
	s_cbranch_execz .LBB0_258
	v_add_f32_e32 v64, v64, v66
	s_lshl_b64 s[12:13], s[12:13], 6
	v_cndmask_b32_e64 v64, 0, v64, s[4:5]
	v_lshl_add_u64 v[128:129], v[124:125], 0, s[12:13]
	v_mov_b32_e32 v66, v65
	v_mov_b32_e32 v67, v65
	global_store_dwordx4 v[128:129], v[64:67], off

.LBB0_265:
	s_min_i32 s7, s8, 0x8000
	s_ashr_i32 s7, s7, 11
	s_mul_hi_i32 s9, s7, 0x6000
	s_mulk_i32 s7, 0x6000
	s_add_u32 s7, s44, s7
	s_addc_u32 s9, s45, s9
	s_add_u32 s10, s7, 0x1000
	s_addc_u32 s11, s9, 0
	v_lshl_add_u64 v[66:67], v[116:117], 2, s[10:11]
	global_load_dwordx4 v[128:131], v[66:67], off
	v_lshl_add_u64 v[212:213], v[118:119], 2, s[10:11]
	global_load_dwordx4 v[200:203], v[212:213], off
	v_lshl_add_u64 v[212:213], v[120:121], 2, s[10:11]
	global_load_dwordx4 v[204:207], v[212:213], off
	v_lshl_add_u64 v[212:213], v[122:123], 2, s[10:11]
	global_load_dwordx4 v[208:211], v[212:213], off
	s_ashr_i32 s9, s8, 31
	s_lshl_b64 s[14:15], s[8:9], 11
	v_lshl_add_u64 v[132:133], v[126:127], 0, s[14:15]
	v_mul_f32_e32 v64, v101, v101
	v_mul_f32_e32 v134, v107, v107
	v_mul_f32_e32 v135, v109, v109
	v_mul_f32_e32 v136, v111, v111
	v_fmac_f32_e32 v64, v100, v100
	v_fmac_f32_e32 v134, v106, v106
	v_mul_f32_e32 v137, v113, v113
	v_mul_f32_e32 v138, v115, v115
	v_fmac_f32_e32 v135, v108, v108
	v_fmac_f32_e32 v136, v110, v110
	v_fmac_f32_e32 v137, v112, v112
	v_fmac_f32_e32 v138, v114, v114
	s_waitcnt vmcnt(0)
	v_pk_add_f32 v[128:129], v[128:129], 1.0 op_sel_hi:[1,0]
	v_pk_add_f32 v[130:131], v[130:131], 1.0 op_sel_hi:[1,0]
	v_pk_mul_f32 v[128:129], v[0:1], v[128:129]
	v_pk_mul_f32 v[130:131], v[2:3], v[130:131]
	v_pk_mul_f32 v[128:129], v[100:101], v[128:129]
	v_pk_mul_f32 v[130:131], v[102:103], v[130:131]
	v_cvt_pk_bf16_f32 v128, v128, v129
	s_nop 0
	v_cvt_pk_bf16_f32 v129, v130, v131
	global_store_dwordx2 v[132:133], v[128:129], off
	v_pk_add_f32 v[200:201], v[200:201], 1.0 op_sel_hi:[1,0]
	v_pk_add_f32 v[202:203], v[202:203], 1.0 op_sel_hi:[1,0]
	v_pk_mul_f32 v[200:201], v[4:5], v[200:201]
	v_pk_mul_f32 v[202:203], v[6:7], v[202:203]
	v_pk_mul_f32 v[200:201], v[104:105], v[200:201]
	v_pk_mul_f32 v[202:203], v[106:107], v[202:203]
	v_cvt_pk_bf16_f32 v200, v200, v201
	s_nop 0
	v_cvt_pk_bf16_f32 v201, v202, v203
	global_store_dwordx2 v[132:133], v[200:201], off offset:512
	v_pk_add_f32 v[204:205], v[204:205], 1.0 op_sel_hi:[1,0]
	v_pk_add_f32 v[206:207], v[206:207], 1.0 op_sel_hi:[1,0]
	v_pk_mul_f32 v[204:205], v[8:9], v[204:205]
	v_pk_mul_f32 v[206:207], v[10:11], v[206:207]
	v_pk_mul_f32 v[204:205], v[108:109], v[204:205]
	v_pk_mul_f32 v[206:207], v[110:111], v[206:207]
	v_cvt_pk_bf16_f32 v204, v204, v205
	s_nop 0
	v_cvt_pk_bf16_f32 v205, v206, v207
	global_store_dwordx2 v[132:133], v[204:205], off offset:1024
	v_mul_f32_e32 v66, v103, v103
	v_mul_f32_e32 v67, v105, v105
	v_fmac_f32_e32 v66, v102, v102
	v_fmac_f32_e32 v67, v104, v104
	v_add_f32_e32 v64, v64, v66
	v_add_f32_e32 v66, v67, v134
	v_add_f32_e32 v67, v135, v136
	v_add_f32_e32 v64, v64, v66
	v_add_f32_e32 v134, v137, v138
	v_add_f32_e32 v64, v64, v67
	v_add_f32_e32 v64, v64, v134
	s_nop 1
	v_add_f32_dpp v64, v64, v64 quad_perm:[1,0,3,2] row_mask:0xf bank_mask:0xf
	s_nop 1
	v_add_f32_dpp v64, v64, v64 quad_perm:[2,3,0,1] row_mask:0xf bank_mask:0xf
	s_nop 1
	v_add_f32_dpp v64, v64, v64 row_half_mirror row_mask:0xf bank_mask:0xf
	s_nop 1
	v_add_f32_dpp v64, v64, v64 row_mirror row_mask:0xf bank_mask:0xf
	ds_swizzle_b32 v66, v64 offset:swizzle(SWAP,16)
	s_waitcnt lgkmcnt(0)
	v_add_f32_e32 v64, v64, v66
	v_mov_b32_e32 v66, v64
	s_nop 1
	v_permlane32_swap_b32_e32 v64, v66
	v_pk_add_f32 v[208:209], v[208:209], 1.0 op_sel_hi:[1,0]
	v_pk_add_f32 v[210:211], v[210:211], 1.0 op_sel_hi:[1,0]
	v_pk_mul_f32 v[208:209], v[12:13], v[208:209]
	v_pk_mul_f32 v[210:211], v[14:15], v[210:211]
	v_pk_mul_f32 v[208:209], v[112:113], v[208:209]
	v_pk_mul_f32 v[210:211], v[114:115], v[210:211]
	v_cvt_pk_bf16_f32 v208, v208, v209
	s_nop 0
	v_cvt_pk_bf16_f32 v209, v210, v211
	global_store_dwordx2 v[132:133], v[208:209], off offset:1536
	s_and_saveexec_b64 s[10:11], s[2:3]
	s_cbranch_execz .LBB0_268
	v_add_f32_e32 v64, v64, v66
	s_lshl_b64 s[8:9], s[8:9], 6
	v_cndmask_b32_e64 v64, 0, v64, s[4:5]
	v_lshl_add_u64 v[128:129], v[124:125], 0, s[8:9]
	v_mov_b32_e32 v66, v65
	v_mov_b32_e32 v67, v65
	global_store_dwordx4 v[128:129], v[64:67], off
	s_or_b64 exec, exec, s[10:11]
	s_add_i32 s8, s0, s6
	s_cmp_gt_i32 s8, 0x8fff
	s_cbranch_scc0 .LBB0_269

.LBB0_269:
	s_min_i32 s7, s8, 0x8000
	s_ashr_i32 s7, s7, 11
	s_mul_hi_i32 s9, s7, 0x6000
	s_mulk_i32 s7, 0x6000
	s_add_u32 s7, s44, s7
	s_addc_u32 s9, s45, s9
	s_add_u32 s10, s7, 0x1000
	s_addc_u32 s11, s9, 0
	v_lshl_add_u64 v[66:67], v[116:117], 2, s[10:11]
	global_load_dwordx4 v[128:131], v[66:67], off
	v_lshl_add_u64 v[212:213], v[118:119], 2, s[10:11]
	global_load_dwordx4 v[200:203], v[212:213], off
	v_lshl_add_u64 v[212:213], v[120:121], 2, s[10:11]
	global_load_dwordx4 v[204:207], v[212:213], off
	v_lshl_add_u64 v[212:213], v[122:123], 2, s[10:11]
	global_load_dwordx4 v[208:211], v[212:213], off
	s_ashr_i32 s9, s8, 31
	s_lshl_b64 s[14:15], s[8:9], 11
	v_lshl_add_u64 v[132:133], v[126:127], 0, s[14:15]
	v_mul_f32_e32 v64, v97, v97
	v_mul_f32_e32 v134, v95, v95
	v_mul_f32_e32 v135, v89, v89
	v_mul_f32_e32 v136, v91, v91
	v_fmac_f32_e32 v64, v96, v96
	v_fmac_f32_e32 v134, v94, v94
	v_mul_f32_e32 v137, v85, v85
	v_mul_f32_e32 v138, v87, v87
	v_fmac_f32_e32 v135, v88, v88
	v_fmac_f32_e32 v136, v90, v90
	v_fmac_f32_e32 v137, v84, v84
	v_fmac_f32_e32 v138, v86, v86
	s_waitcnt vmcnt(0)
	v_pk_add_f32 v[128:129], v[128:129], 1.0 op_sel_hi:[1,0]
	v_pk_add_f32 v[130:131], v[130:131], 1.0 op_sel_hi:[1,0]
	v_pk_mul_f32 v[128:129], v[0:1], v[128:129]
	v_pk_mul_f32 v[130:131], v[2:3], v[130:131]
	v_pk_mul_f32 v[128:129], v[96:97], v[128:129]
	v_pk_mul_f32 v[130:131], v[98:99], v[130:131]
	v_cvt_pk_bf16_f32 v128, v128, v129
	s_nop 0
	v_cvt_pk_bf16_f32 v129, v130, v131
	global_store_dwordx2 v[132:133], v[128:129], off
	v_pk_add_f32 v[200:201], v[200:201], 1.0 op_sel_hi:[1,0]
	v_pk_add_f32 v[202:203], v[202:203], 1.0 op_sel_hi:[1,0]
	v_pk_mul_f32 v[200:201], v[4:5], v[200:201]
	v_pk_mul_f32 v[202:203], v[6:7], v[202:203]
	v_pk_mul_f32 v[200:201], v[92:93], v[200:201]
	v_pk_mul_f32 v[202:203], v[94:95], v[202:203]
	v_cvt_pk_bf16_f32 v200, v200, v201
	s_nop 0
	v_cvt_pk_bf16_f32 v201, v202, v203
	global_store_dwordx2 v[132:133], v[200:201], off offset:512
	v_pk_add_f32 v[204:205], v[204:205], 1.0 op_sel_hi:[1,0]
	v_pk_add_f32 v[206:207], v[206:207], 1.0 op_sel_hi:[1,0]
	v_pk_mul_f32 v[204:205], v[8:9], v[204:205]
	v_pk_mul_f32 v[206:207], v[10:11], v[206:207]
	v_pk_mul_f32 v[204:205], v[88:89], v[204:205]
	v_pk_mul_f32 v[206:207], v[90:91], v[206:207]
	v_cvt_pk_bf16_f32 v204, v204, v205
	s_nop 0
	v_cvt_pk_bf16_f32 v205, v206, v207
	global_store_dwordx2 v[132:133], v[204:205], off offset:1024
	v_mul_f32_e32 v66, v99, v99
	v_mul_f32_e32 v67, v93, v93
	v_fmac_f32_e32 v66, v98, v98
	v_fmac_f32_e32 v67, v92, v92
	v_add_f32_e32 v64, v64, v66
	v_add_f32_e32 v66, v67, v134
	v_add_f32_e32 v67, v135, v136
	v_add_f32_e32 v64, v64, v66
	v_add_f32_e32 v134, v137, v138
	v_add_f32_e32 v64, v64, v67
	v_add_f32_e32 v64, v64, v134
	s_nop 1
	v_add_f32_dpp v64, v64, v64 quad_perm:[1,0,3,2] row_mask:0xf bank_mask:0xf
	s_nop 1
	v_add_f32_dpp v64, v64, v64 quad_perm:[2,3,0,1] row_mask:0xf bank_mask:0xf
	s_nop 1
	v_add_f32_dpp v64, v64, v64 row_half_mirror row_mask:0xf bank_mask:0xf
	s_nop 1
	v_add_f32_dpp v64, v64, v64 row_mirror row_mask:0xf bank_mask:0xf
	ds_swizzle_b32 v66, v64 offset:swizzle(SWAP,16)
	s_waitcnt lgkmcnt(0)
	v_add_f32_e32 v64, v64, v66
	v_mov_b32_e32 v66, v64
	s_nop 1
	v_permlane32_swap_b32_e32 v64, v66
	v_pk_add_f32 v[208:209], v[208:209], 1.0 op_sel_hi:[1,0]
	v_pk_add_f32 v[210:211], v[210:211], 1.0 op_sel_hi:[1,0]
	v_pk_mul_f32 v[208:209], v[12:13], v[208:209]
	v_pk_mul_f32 v[210:211], v[14:15], v[210:211]
	v_pk_mul_f32 v[208:209], v[84:85], v[208:209]
	v_pk_mul_f32 v[210:211], v[86:87], v[210:211]
	v_cvt_pk_bf16_f32 v208, v208, v209
	s_nop 0
	v_cvt_pk_bf16_f32 v209, v210, v211
	global_store_dwordx2 v[132:133], v[208:209], off offset:1536
	s_and_saveexec_b64 s[10:11], s[2:3]
	s_cbranch_execz .LBB0_271
	v_add_f32_e32 v64, v64, v66
	s_lshl_b64 s[8:9], s[8:9], 6
	v_cndmask_b32_e64 v64, 0, v64, s[4:5]
	v_lshl_add_u64 v[128:129], v[124:125], 0, s[8:9]
	v_mov_b32_e32 v66, v65
	v_mov_b32_e32 v67, v65
	global_store_dwordx4 v[128:129], v[64:67], off

.LBB0_272:
	s_min_i32 s7, s6, 0x8000
	s_ashr_i32 s7, s7, 11
	s_mul_hi_i32 s8, s7, 0x6000
	s_mulk_i32 s7, 0x6000
	s_add_u32 s7, s44, s7
	s_addc_u32 s9, s45, s8
	s_add_u32 s8, s7, 0x1000
	s_addc_u32 s9, s9, 0
	v_lshl_add_u64 v[66:67], v[116:117], 2, s[8:9]
	global_load_dwordx4 v[128:131], v[66:67], off
	v_lshl_add_u64 v[212:213], v[118:119], 2, s[8:9]
	global_load_dwordx4 v[200:203], v[212:213], off
	v_lshl_add_u64 v[212:213], v[120:121], 2, s[8:9]
	global_load_dwordx4 v[204:207], v[212:213], off
	v_lshl_add_u64 v[212:213], v[122:123], 2, s[8:9]
	global_load_dwordx4 v[208:211], v[212:213], off
	s_ashr_i32 s7, s6, 31
	s_lshl_b64 s[10:11], s[6:7], 11
	v_lshl_add_u64 v[132:133], v[126:127], 0, s[10:11]
	v_mul_f32_e32 v64, v81, v81
	v_mul_f32_e32 v134, v79, v79
	v_mul_f32_e32 v135, v73, v73
	v_mul_f32_e32 v136, v75, v75
	v_fmac_f32_e32 v64, v80, v80
	v_fmac_f32_e32 v134, v78, v78
	v_mul_f32_e32 v137, v69, v69
	v_mul_f32_e32 v138, v71, v71
	v_fmac_f32_e32 v135, v72, v72
	v_fmac_f32_e32 v136, v74, v74
	v_fmac_f32_e32 v137, v68, v68
	v_fmac_f32_e32 v138, v70, v70
	s_waitcnt vmcnt(0)
	v_pk_add_f32 v[128:129], v[128:129], 1.0 op_sel_hi:[1,0]
	v_pk_add_f32 v[130:131], v[130:131], 1.0 op_sel_hi:[1,0]
	v_pk_mul_f32 v[128:129], v[0:1], v[128:129]
	v_pk_mul_f32 v[130:131], v[2:3], v[130:131]
	v_pk_mul_f32 v[128:129], v[80:81], v[128:129]
	v_pk_mul_f32 v[130:131], v[82:83], v[130:131]
	v_cvt_pk_bf16_f32 v128, v128, v129
	s_nop 0
	v_cvt_pk_bf16_f32 v129, v130, v131
	global_store_dwordx2 v[132:133], v[128:129], off
	v_pk_add_f32 v[200:201], v[200:201], 1.0 op_sel_hi:[1,0]
	v_pk_add_f32 v[202:203], v[202:203], 1.0 op_sel_hi:[1,0]
	v_pk_mul_f32 v[200:201], v[4:5], v[200:201]
	v_pk_mul_f32 v[202:203], v[6:7], v[202:203]
	v_pk_mul_f32 v[200:201], v[76:77], v[200:201]
	v_pk_mul_f32 v[202:203], v[78:79], v[202:203]
	v_cvt_pk_bf16_f32 v200, v200, v201
	s_nop 0
	v_cvt_pk_bf16_f32 v201, v202, v203
	global_store_dwordx2 v[132:133], v[200:201], off offset:512
	v_pk_add_f32 v[204:205], v[204:205], 1.0 op_sel_hi:[1,0]
	v_pk_add_f32 v[206:207], v[206:207], 1.0 op_sel_hi:[1,0]
	v_pk_mul_f32 v[204:205], v[8:9], v[204:205]
	v_pk_mul_f32 v[206:207], v[10:11], v[206:207]
	v_pk_mul_f32 v[204:205], v[72:73], v[204:205]
	v_pk_mul_f32 v[206:207], v[74:75], v[206:207]
	v_cvt_pk_bf16_f32 v204, v204, v205
	s_nop 0
	v_cvt_pk_bf16_f32 v205, v206, v207
	global_store_dwordx2 v[132:133], v[204:205], off offset:1024
	v_mul_f32_e32 v66, v83, v83
	v_mul_f32_e32 v67, v77, v77
	v_fmac_f32_e32 v66, v82, v82
	v_fmac_f32_e32 v67, v76, v76
	v_add_f32_e32 v64, v64, v66
	v_add_f32_e32 v66, v67, v134
	v_add_f32_e32 v67, v135, v136
	v_add_f32_e32 v64, v64, v66
	v_add_f32_e32 v134, v137, v138
	v_add_f32_e32 v64, v64, v67
	v_add_f32_e32 v64, v64, v134
	s_nop 1
	v_add_f32_dpp v64, v64, v64 quad_perm:[1,0,3,2] row_mask:0xf bank_mask:0xf
	s_nop 1
	v_add_f32_dpp v64, v64, v64 quad_perm:[2,3,0,1] row_mask:0xf bank_mask:0xf
	s_nop 1
	v_add_f32_dpp v64, v64, v64 row_half_mirror row_mask:0xf bank_mask:0xf
	s_nop 1
	v_add_f32_dpp v64, v64, v64 row_mirror row_mask:0xf bank_mask:0xf
	ds_swizzle_b32 v66, v64 offset:swizzle(SWAP,16)
	s_waitcnt lgkmcnt(0)
	v_add_f32_e32 v64, v64, v66
	v_mov_b32_e32 v66, v64
	s_nop 1
	v_permlane32_swap_b32_e32 v64, v66
	v_pk_add_f32 v[208:209], v[208:209], 1.0 op_sel_hi:[1,0]
	v_pk_add_f32 v[210:211], v[210:211], 1.0 op_sel_hi:[1,0]
	v_pk_mul_f32 v[208:209], v[12:13], v[208:209]
	v_pk_mul_f32 v[210:211], v[14:15], v[210:211]
	v_pk_mul_f32 v[208:209], v[68:69], v[208:209]
	v_pk_mul_f32 v[210:211], v[70:71], v[210:211]
	v_cvt_pk_bf16_f32 v208, v208, v209
	s_nop 0
	v_cvt_pk_bf16_f32 v209, v210, v211
	global_store_dwordx2 v[132:133], v[208:209], off offset:1536
	s_and_saveexec_b64 s[8:9], s[2:3]
	s_cbranch_execz .LBB0_242
	v_add_f32_e32 v64, v64, v66
	s_lshl_b64 s[6:7], s[6:7], 6
	v_cndmask_b32_e64 v64, 0, v64, s[4:5]
	v_lshl_add_u64 v[128:129], v[124:125], 0, s[6:7]
	v_mov_b32_e32 v66, v65
	v_mov_b32_e32 v67, v65
	global_store_dwordx4 v[128:129], v[64:67], off
	s_branch .LBB0_242
